# phase-1 DMA ring streams across tile boundaries (next tile A0/B0/A1 requested during the last two K stages; stale epilogue waits removed) + o-norm two rows per iteration
# speedup vs baseline: 1.1235x; 1.0068x over previous
.LBB0_112:
	v_writelane_b32 v237, s48, 51
	v_writelane_b32 v237, s44, 52
	s_nop 1
	v_writelane_b32 v237, s45, 53
	s_or_b64 exec, exec, s[0:1]
	s_add_u32 s74, s54, 0x2200000
	s_addc_u32 s75, s55, 0
	s_and_b32 s0, s72, 7
	s_cmp_lg_u32 s0, 0
	s_cselect_b64 s[50:51], -1, 0
	s_ashr_i32 s2, s96, 3
	s_ashr_i32 s3, s72, 3
	s_and_b32 s1, s96, 7
	s_cmp_eq_u32 s0, 0
	s_cselect_b64 s[4:5], -1, 0
	v_writelane_b32 v237, s1, 54
	s_mul_i32 s19, s1, 17
	v_writelane_b32 v237, s4, 55
	s_and_b64 s[0:1], s[4:5], exec
	s_movk_i32 s0, 0x1dc
	v_writelane_b32 v237, s5, 56
	s_cselect_b32 s49, s2, s96
	s_cselect_b32 s12, s0, 0xee0
	v_writelane_b32 v237, s3, 57
	s_cselect_b32 s48, s3, s72
	s_cmp_ge_i32 s49, s12
	v_and_b32_e32 v174, 15, v0
	s_barrier
	v_writelane_b32 v237, s2, 58
	s_cbranch_scc1 .LBB0_130
	v_lshrrev_b32_e32 v8, 3, v0
	v_lshlrev_b32_e32 v2, 11, v8
	v_mov_b32_e32 v3, 0
	v_lshl_add_u64 v[4:5], s[54:55], 0, v[2:3]
	v_lshlrev_b32_e32 v2, 4, v0
	v_and_b32_e32 v2, 0x70, v2
	v_lshl_add_u64 v[98:99], v[4:5], 0, v[2:3]
	v_xor_b32_e32 v4, v8, v0
	s_movk_i32 s4, 0x70
	v_lshlrev_b32_e32 v2, 7, v8
	v_lshlrev_b32_e32 v4, 4, v4
	v_lshrrev_b32_e32 v6, 4, v0
	v_and_or_b32 v108, v4, s4, v2
	v_and_b32_e32 v4, 7, v0
	v_bitop3_b32 v5, v6, v4, 3 bitop3:0x6c
	v_bfe_u32 v7, v0, 4, 2
	v_lshlrev_b32_e32 v109, 4, v5
	v_lshlrev_b32_e32 v5, 7, v0
	v_and_b32_e32 v112, 0x2780, v5
	v_bitop3_b32 v5, v7, v4, 4 bitop3:0x36
	s_mov_b64 s[2:3], 0xe680000
	v_lshrrev_b32_e32 v2, 1, v0
	v_lshlrev_b32_e32 v113, 4, v5
	v_and_b32_e32 v5, 64, v0
	v_lshl_add_u64 v[100:101], v[98:99], 0, s[2:3]
	v_and_or_b32 v110, v2, 64, v174
	v_and_or_b32 v114, v2, 24, v5
	v_lshlrev_b32_e32 v2, 8, v0
	v_lshlrev_b32_e32 v4, 4, v4
	s_mov_b32 s2, 0xf800
	s_add_u32 s0, s54, 0xf280000
	v_and_or_b32 v2, v2, s2, v4
	s_addc_u32 s1, s55, 0
	s_add_i32 s13, s19, 9
	v_lshlrev_b32_e32 v111, 7, v110
	v_lshl_add_u64 v[102:103], s[54:55], 0, v[2:3]
	s_mov_b32 s14, 0x10000
	s_mov_b32 s15, 0x20000
	s_mov_b32 s16, 0x30000
	s_movk_i32 s17, 0x1c00
	s_mov_b32 s18, s49
	v_lshrrev_b32_e32 v104, 3, v0
	v_lshlrev_b32_e32 v104, 11, v104
	v_and_b32_e32 v105, 0x70, v108
	v_or_b32_e32 v104, v104, v105
	v_add_u32_e32 v105, 0x10000, v104
	v_add_u32_e32 v106, 0x20000, v104
	v_add_u32_e32 v107, 0x30000, v104
	v_add_u32_e32 v98, v109, v111
	v_add_u32_e32 v99, v113, v111
	v_add_u32_e32 v100, v109, v112
	v_add_u32_e32 v101, v113, v112
	v_lshrrev_b32_e32 v115, 6, v0
	s_nop 1
	v_readfirstlane_b32 s30, v115
	s_nop 3
	s_lshl_b32 s30, s30, 10
	s_mov_b32 s40, 0
	s_branch .LBB0_115
.LBB0_114:
	v_add_u32_e32 v54, s4, v110
	v_ashrrev_i32_e32 v55, 31, v54
	v_lshl_add_u64 v[38:39], v[54:55], 2, s[0:1]
	v_or_b32_e32 v40, s2, v114
	v_mov_b64_e32 v[56:57], s[74:75]
	v_ashrrev_i32_e32 v41, 31, v40
	v_mad_i64_i32 v[42:43], s[2:3], v54, s17, v[56:57]
	v_lshlrev_b64 v[64:65], 1, v[40:41]
	v_or_b32_e32 v62, 16, v54
	v_lshl_add_u64 v[66:67], v[42:43], 0, v[64:65]
	v_ashrrev_i32_e32 v63, 31, v62
	v_lshl_add_u64 v[68:69], v[62:63], 2, s[0:1]
	s_add_i32 s18, s18, s48
	s_cmp_lt_i32 s18, s12
	v_pk_mul_f32 v[40:41], v[94:95], v[142:143] op_sel_hi:[1,0]
	v_pk_mul_f32 v[42:43], v[96:97], v[142:143] op_sel_hi:[1,0]
	v_pk_mul_f32 v[44:45], v[90:91], v[142:143] op_sel_hi:[1,0]
	v_pk_mul_f32 v[70:71], v[92:93], v[142:143] op_sel_hi:[1,0]
	v_pk_mul_f32 v[72:73], v[86:87], v[142:143] op_sel_hi:[1,0]
	v_pk_mul_f32 v[74:75], v[88:89], v[142:143] op_sel_hi:[1,0]
	v_pk_mul_f32 v[76:77], v[82:83], v[142:143] op_sel_hi:[1,0]
	v_pk_mul_f32 v[78:79], v[84:85], v[142:143] op_sel_hi:[1,0]
	v_cvt_pk_bf16_f32 v38, v40, v41
	v_cvt_pk_bf16_f32 v39, v42, v43
	v_cvt_pk_bf16_f32 v40, v44, v45
	v_cvt_pk_bf16_f32 v41, v70, v71
	v_cvt_pk_bf16_f32 v42, v72, v73
	v_cvt_pk_bf16_f32 v43, v74, v75
	v_cvt_pk_bf16_f32 v44, v76, v77
	v_cvt_pk_bf16_f32 v45, v78, v79
	global_store_dwordx4 v[66:67], v[38:41], off
	global_store_dwordx4 v[66:67], v[42:45], off offset:64
	s_nop 1
	v_mad_i64_i32 v[40:41], s[2:3], v62, s17, v[56:57]
	v_or_b32_e32 v42, 32, v54
	v_lshl_add_u64 v[44:45], v[40:41], 0, v[64:65]
	v_ashrrev_i32_e32 v43, 31, v42
	v_lshl_add_u64 v[62:63], v[42:43], 2, s[0:1]
	v_pk_mul_f32 v[40:41], v[58:59], v[144:145] op_sel_hi:[1,0]
	v_pk_mul_f32 v[58:59], v[60:61], v[144:145] op_sel_hi:[1,0]
	v_pk_mul_f32 v[50:51], v[50:51], v[144:145] op_sel_hi:[1,0]
	v_pk_mul_f32 v[52:53], v[52:53], v[144:145] op_sel_hi:[1,0]
	v_pk_mul_f32 v[46:47], v[46:47], v[144:145] op_sel_hi:[1,0]
	v_pk_mul_f32 v[48:49], v[48:49], v[144:145] op_sel_hi:[1,0]
	v_pk_mul_f32 v[60:61], v[34:35], v[144:145] op_sel_hi:[1,0]
	v_pk_mul_f32 v[66:67], v[36:37], v[144:145] op_sel_hi:[1,0]
	v_cvt_pk_bf16_f32 v34, v40, v41
	v_cvt_pk_bf16_f32 v35, v58, v59
	v_cvt_pk_bf16_f32 v36, v50, v51
	v_cvt_pk_bf16_f32 v37, v52, v53
	v_cvt_pk_bf16_f32 v38, v46, v47
	v_cvt_pk_bf16_f32 v39, v48, v49
	v_cvt_pk_bf16_f32 v40, v60, v61
	v_cvt_pk_bf16_f32 v41, v66, v67
	global_store_dwordx4 v[44:45], v[34:37], off
	global_store_dwordx4 v[44:45], v[38:41], off offset:64
	s_nop 1
	v_or_b32_e32 v36, 48, v54
	v_mad_i64_i32 v[38:39], s[2:3], v42, s17, v[56:57]
	v_ashrrev_i32_e32 v37, 31, v36
	v_lshl_add_u64 v[38:39], v[38:39], 0, v[64:65]
	v_lshl_add_u64 v[40:41], v[36:37], 2, s[0:1]
	v_pk_mul_f32 v[30:31], v[30:31], v[146:147] op_sel_hi:[1,0]
	v_pk_mul_f32 v[32:33], v[32:33], v[146:147] op_sel_hi:[1,0]
	v_pk_mul_f32 v[26:27], v[26:27], v[146:147] op_sel_hi:[1,0]
	v_pk_mul_f32 v[28:29], v[28:29], v[146:147] op_sel_hi:[1,0]
	v_pk_mul_f32 v[22:23], v[22:23], v[146:147] op_sel_hi:[1,0]
	v_pk_mul_f32 v[24:25], v[24:25], v[146:147] op_sel_hi:[1,0]
	v_pk_mul_f32 v[42:43], v[18:19], v[146:147] op_sel_hi:[1,0]
	v_pk_mul_f32 v[34:35], v[20:21], v[146:147] op_sel_hi:[1,0]
	v_cvt_pk_bf16_f32 v18, v30, v31
	v_cvt_pk_bf16_f32 v19, v32, v33
	v_cvt_pk_bf16_f32 v20, v26, v27
	v_cvt_pk_bf16_f32 v21, v28, v29
	v_cvt_pk_bf16_f32 v22, v22, v23
	v_cvt_pk_bf16_f32 v23, v24, v25
	v_cvt_pk_bf16_f32 v24, v42, v43
	v_cvt_pk_bf16_f32 v25, v34, v35
	global_store_dwordx4 v[38:39], v[18:21], off
	global_store_dwordx4 v[38:39], v[22:25], off offset:64
	s_nop 1
	v_mad_i64_i32 v[20:21], s[2:3], v36, s17, v[56:57]
	v_lshl_add_u64 v[20:21], v[20:21], 0, v[64:65]
	v_pk_mul_f32 v[14:15], v[14:15], v[148:149] op_sel_hi:[1,0]
	v_pk_mul_f32 v[16:17], v[16:17], v[148:149] op_sel_hi:[1,0]
	v_pk_mul_f32 v[10:11], v[10:11], v[148:149] op_sel_hi:[1,0]
	v_pk_mul_f32 v[12:13], v[12:13], v[148:149] op_sel_hi:[1,0]
	v_pk_mul_f32 v[6:7], v[6:7], v[148:149] op_sel_hi:[1,0]
	v_pk_mul_f32 v[8:9], v[8:9], v[148:149] op_sel_hi:[1,0]
	v_pk_mul_f32 v[22:23], v[2:3], v[148:149] op_sel_hi:[1,0]
	v_pk_mul_f32 v[18:19], v[4:5], v[148:149] op_sel_hi:[1,0]
	v_cvt_pk_bf16_f32 v2, v14, v15
	v_cvt_pk_bf16_f32 v3, v16, v17
	v_cvt_pk_bf16_f32 v4, v10, v11
	v_cvt_pk_bf16_f32 v5, v12, v13
	v_cvt_pk_bf16_f32 v6, v6, v7
	v_cvt_pk_bf16_f32 v7, v8, v9
	v_cvt_pk_bf16_f32 v8, v22, v23
	v_cvt_pk_bf16_f32 v9, v18, v19
	global_store_dwordx4 v[20:21], v[2:5], off
	global_store_dwordx4 v[20:21], v[6:9], off offset:64
	s_nop 1
	s_cbranch_scc0 .LBB0_130

.LBB0_122:
	s_lshl_b32 s4, s4, 7
	v_add_u32_e32 v150, s4, v110
	v_ashrrev_i32_e32 v151, 31, v150
	v_lshl_add_u64 v[150:151], v[150:151], 2, s[0:1]
	global_load_dword v142, v[150:151], off
	global_load_dword v144, v[150:151], off offset:64
	global_load_dword v146, v[150:151], off offset:128
	global_load_dword v148, v[150:151], off offset:192
	s_lshl_b32 s2, s5, 7
	s_cmp_eq_u32 s40, 1
	s_cbranch_scc1 .Lg1_pref
	s_lshl_b32 s24, s4, 11
	s_add_u32 s26, s54, s24
	s_addc_u32 s27, s55, 0
	s_lshl_b32 s24, s2, 11
	s_add_u32 s28, s54, s24
	s_addc_u32 s29, s55, 0
	s_add_u32 s28, s28, 0xe680000
	s_addc_u32 s29, s29, 0
	s_barrier
	s_mov_b32 m0, s30
	s_nop 0
	global_load_lds_dwordx4 v104, s[26:27]
	s_add_u32 m0, s30, 0x1000
	s_nop 0
	global_load_lds_dwordx4 v105, s[26:27]
	s_add_u32 m0, s30, 0x2000
	s_nop 0
	global_load_lds_dwordx4 v106, s[26:27]
	s_add_u32 m0, s30, 0x3000
	s_nop 0
	global_load_lds_dwordx4 v107, s[26:27]
	s_add_u32 s31, s30, 0x4000
	s_mov_b32 m0, s31
	s_nop 0
	global_load_lds_dwordx4 v104, s[28:29]
	s_add_u32 m0, s31, 0x1000
	s_nop 0
	global_load_lds_dwordx4 v105, s[28:29]
	s_add_u32 m0, s31, 0x2000
	s_nop 0
	global_load_lds_dwordx4 v106, s[28:29]
	s_add_u32 m0, s31, 0x3000
	s_nop 0
	global_load_lds_dwordx4 v107, s[28:29]
	s_add_u32 s26, s26, 0x80
	s_addc_u32 s27, s27, 0
	s_add_u32 s31, s30, 0x8000
	s_mov_b32 m0, s31
	s_nop 0
	global_load_lds_dwordx4 v104, s[26:27]
	s_add_u32 m0, s31, 0x1000
	s_nop 0
	global_load_lds_dwordx4 v105, s[26:27]
	s_add_u32 m0, s31, 0x2000
	s_nop 0
	global_load_lds_dwordx4 v106, s[26:27]
	s_add_u32 m0, s31, 0x3000
	s_nop 0
	global_load_lds_dwordx4 v107, s[26:27]
	v_mov_b32_e32 v2, 0
	v_mov_b32_e32 v3, v2
	v_mov_b32_e32 v4, v2
	v_mov_b32_e32 v5, v2
	v_mov_b32_e32 v6, v2
	v_mov_b32_e32 v7, v2
	v_mov_b32_e32 v8, v2
	v_mov_b32_e32 v9, v2
	v_mov_b32_e32 v10, v2
	v_mov_b32_e32 v11, v2
	v_mov_b32_e32 v12, v2
	v_mov_b32_e32 v13, v2
	v_mov_b32_e32 v14, v2
	v_mov_b32_e32 v15, v2
	v_mov_b32_e32 v16, v2
	v_mov_b32_e32 v17, v2
	v_mov_b32_e32 v18, v2
	v_mov_b32_e32 v19, v2
	v_mov_b32_e32 v20, v2
	v_mov_b32_e32 v21, v2
	v_mov_b32_e32 v22, v2
	v_mov_b32_e32 v23, v2
	v_mov_b32_e32 v24, v2
	v_mov_b32_e32 v25, v2
	v_mov_b32_e32 v26, v2
	v_mov_b32_e32 v27, v2
	v_mov_b32_e32 v28, v2
	v_mov_b32_e32 v29, v2
	v_mov_b32_e32 v30, v2
	v_mov_b32_e32 v31, v2
	v_mov_b32_e32 v32, v2
	v_mov_b32_e32 v33, v2
	v_mov_b32_e32 v34, v2
	v_mov_b32_e32 v35, v2
	v_mov_b32_e32 v36, v2
	v_mov_b32_e32 v37, v2
	v_mov_b32_e32 v46, v2
	v_mov_b32_e32 v47, v2
	v_mov_b32_e32 v48, v2
	v_mov_b32_e32 v49, v2
	v_mov_b32_e32 v50, v2
	v_mov_b32_e32 v51, v2
	v_mov_b32_e32 v52, v2
	v_mov_b32_e32 v53, v2
	v_mov_b32_e32 v58, v2
	v_mov_b32_e32 v59, v2
	v_mov_b32_e32 v60, v2
	v_mov_b32_e32 v61, v2
	v_mov_b32_e32 v82, v2
	v_mov_b32_e32 v83, v2
	v_mov_b32_e32 v84, v2
	v_mov_b32_e32 v85, v2
	v_mov_b32_e32 v86, v2
	v_mov_b32_e32 v87, v2
	v_mov_b32_e32 v88, v2
	v_mov_b32_e32 v89, v2
	v_mov_b32_e32 v90, v2
	v_mov_b32_e32 v91, v2
	v_mov_b32_e32 v92, v2
	v_mov_b32_e32 v93, v2
	v_mov_b32_e32 v94, v2
	v_mov_b32_e32 v95, v2
	v_mov_b32_e32 v96, v2
	v_mov_b32_e32 v97, v2
	s_mov_b32 s3, 0
	s_mov_b32 s10, 0
	s_mov_b32 s11, 0x4000
	s_waitcnt vmcnt(4)
	s_barrier
	s_branch .Lg1_loop
.Lg1_pref:
	v_mov_b32_e32 v2, 0
	v_mov_b32_e32 v3, v2
	v_mov_b32_e32 v4, v2
	v_mov_b32_e32 v5, v2
	v_mov_b32_e32 v6, v2
	v_mov_b32_e32 v7, v2
	v_mov_b32_e32 v8, v2
	v_mov_b32_e32 v9, v2
	v_mov_b32_e32 v10, v2
	v_mov_b32_e32 v11, v2
	v_mov_b32_e32 v12, v2
	v_mov_b32_e32 v13, v2
	v_mov_b32_e32 v14, v2
	v_mov_b32_e32 v15, v2
	v_mov_b32_e32 v16, v2
	v_mov_b32_e32 v17, v2
	v_mov_b32_e32 v18, v2
	v_mov_b32_e32 v19, v2
	v_mov_b32_e32 v20, v2
	v_mov_b32_e32 v21, v2
	v_mov_b32_e32 v22, v2
	v_mov_b32_e32 v23, v2
	v_mov_b32_e32 v24, v2
	v_mov_b32_e32 v25, v2
	v_mov_b32_e32 v26, v2
	v_mov_b32_e32 v27, v2
	v_mov_b32_e32 v28, v2
	v_mov_b32_e32 v29, v2
	v_mov_b32_e32 v30, v2
	v_mov_b32_e32 v31, v2
	v_mov_b32_e32 v32, v2
	v_mov_b32_e32 v33, v2
	v_mov_b32_e32 v34, v2
	v_mov_b32_e32 v35, v2
	v_mov_b32_e32 v36, v2
	v_mov_b32_e32 v37, v2
	v_mov_b32_e32 v46, v2
	v_mov_b32_e32 v47, v2
	v_mov_b32_e32 v48, v2
	v_mov_b32_e32 v49, v2
	v_mov_b32_e32 v50, v2
	v_mov_b32_e32 v51, v2
	v_mov_b32_e32 v52, v2
	v_mov_b32_e32 v53, v2
	v_mov_b32_e32 v58, v2
	v_mov_b32_e32 v59, v2
	v_mov_b32_e32 v60, v2
	v_mov_b32_e32 v61, v2
	v_mov_b32_e32 v82, v2
	v_mov_b32_e32 v83, v2
	v_mov_b32_e32 v84, v2
	v_mov_b32_e32 v85, v2
	v_mov_b32_e32 v86, v2
	v_mov_b32_e32 v87, v2
	v_mov_b32_e32 v88, v2
	v_mov_b32_e32 v89, v2
	v_mov_b32_e32 v90, v2
	v_mov_b32_e32 v91, v2
	v_mov_b32_e32 v92, v2
	v_mov_b32_e32 v93, v2
	v_mov_b32_e32 v94, v2
	v_mov_b32_e32 v95, v2
	v_mov_b32_e32 v96, v2
	v_mov_b32_e32 v97, v2
	s_mov_b32 s3, 0
	s_waitcnt vmcnt(16)
	s_barrier
.Lg1_loop:
	v_add_u32_e32 v136, s11, v100
	ds_read_b128 v[116:119], v136
	v_add_u32_e32 v115, s10, v98
	ds_read_b128 v[120:123], v136 offset:2048
	ds_read_b128 v[124:127], v115
	ds_read_b128 v[128:131], v115 offset:2048
	ds_read_b128 v[132:135], v136 offset:4096
	ds_read_b128 v[136:139], v136 offset:6144
	s_add_u32 s28, s28, 0x80
	s_addc_u32 s29, s29, 0
	s_add_u32 s31, s10, 0xc000
	s_sub_u32 s25, s31, 0x14000
	s_cmp_ge_u32 s31, 0x14000
	s_cselect_b32 s31, s25, s31
	s_add_u32 s31, s31, s30
	s_add_u32 s26, s26, 0x80
	s_addc_u32 s27, s27, 0
	s_add_u32 s24, s10, 0x10000
	s_sub_u32 s25, s24, 0x14000
	s_cmp_ge_u32 s24, 0x14000
	s_cselect_b32 s24, s25, s24
	s_add_u32 s24, s24, s30
	s_mov_b32 m0, s31
	s_nop 0
	global_load_lds_dwordx4 v104, s[28:29]
	s_waitcnt lgkmcnt(3)
	v_mfma_f32_16x16x32_bf16 v[90:93], v[120:123], v[124:127], v[90:93]
	v_mfma_f32_16x16x32_bf16 v[94:97], v[116:119], v[124:127], v[94:97]
	s_waitcnt lgkmcnt(1)
	v_mfma_f32_16x16x32_bf16 v[86:89], v[132:135], v[124:127], v[86:89]
	s_waitcnt lgkmcnt(0)
	v_mfma_f32_16x16x32_bf16 v[82:85], v[136:139], v[124:127], v[82:85]
	s_add_u32 m0, s31, 0x1000
	s_nop 0
	global_load_lds_dwordx4 v105, s[28:29]
	v_mfma_f32_16x16x32_bf16 v[58:61], v[116:119], v[128:131], v[58:61]
	v_mfma_f32_16x16x32_bf16 v[50:53], v[120:123], v[128:131], v[50:53]
	v_mfma_f32_16x16x32_bf16 v[46:49], v[132:135], v[128:131], v[46:49]
	v_mfma_f32_16x16x32_bf16 v[34:37], v[136:139], v[128:131], v[34:37]
	ds_read_b128 v[124:127], v115 offset:4096
	ds_read_b128 v[128:131], v115 offset:6144
	v_add_u32_e32 v140, s11, v101
	s_add_u32 m0, s31, 0x2000
	s_nop 0
	global_load_lds_dwordx4 v106, s[28:29]
	s_waitcnt lgkmcnt(1)
	v_mfma_f32_16x16x32_bf16 v[30:33], v[116:119], v[124:127], v[30:33]
	v_add_u32_e32 v115, s10, v99
	v_mfma_f32_16x16x32_bf16 v[26:29], v[120:123], v[124:127], v[26:29]
	v_mfma_f32_16x16x32_bf16 v[22:25], v[132:135], v[124:127], v[22:25]
	v_mfma_f32_16x16x32_bf16 v[18:21], v[136:139], v[124:127], v[18:21]
	s_add_u32 m0, s31, 0x3000
	s_nop 0
	global_load_lds_dwordx4 v107, s[28:29]
	s_waitcnt lgkmcnt(0)
	v_mfma_f32_16x16x32_bf16 v[14:17], v[116:119], v[128:131], v[14:17]
	ds_read_b128 v[116:119], v140
	v_mfma_f32_16x16x32_bf16 v[10:13], v[120:123], v[128:131], v[10:13]
	v_mfma_f32_16x16x32_bf16 v[6:9], v[132:135], v[128:131], v[6:9]
	v_mfma_f32_16x16x32_bf16 v[2:5], v[136:139], v[128:131], v[2:5]
	ds_read_b128 v[120:123], v140 offset:2048
	ds_read_b128 v[124:127], v115
	ds_read_b128 v[128:131], v115 offset:2048
	ds_read_b128 v[132:135], v140 offset:4096
	ds_read_b128 v[136:139], v140 offset:6144
	s_mov_b32 m0, s24
	s_nop 0
	global_load_lds_dwordx4 v104, s[26:27]
	s_waitcnt lgkmcnt(3)
	v_mfma_f32_16x16x32_bf16 v[94:97], v[116:119], v[124:127], v[94:97]
	v_mfma_f32_16x16x32_bf16 v[90:93], v[120:123], v[124:127], v[90:93]
	s_waitcnt lgkmcnt(1)
	v_mfma_f32_16x16x32_bf16 v[86:89], v[132:135], v[124:127], v[86:89]
	s_waitcnt lgkmcnt(0)
	v_mfma_f32_16x16x32_bf16 v[82:85], v[136:139], v[124:127], v[82:85]
	s_add_u32 m0, s24, 0x1000
	s_nop 0
	global_load_lds_dwordx4 v105, s[26:27]
	v_mfma_f32_16x16x32_bf16 v[58:61], v[116:119], v[128:131], v[58:61]
	v_mfma_f32_16x16x32_bf16 v[50:53], v[120:123], v[128:131], v[50:53]
	v_mfma_f32_16x16x32_bf16 v[46:49], v[132:135], v[128:131], v[46:49]
	v_mfma_f32_16x16x32_bf16 v[34:37], v[136:139], v[128:131], v[34:37]
	ds_read_b128 v[124:127], v115 offset:4096
	ds_read_b128 v[128:131], v115 offset:6144
	s_add_u32 m0, s24, 0x2000
	s_nop 0
	global_load_lds_dwordx4 v106, s[26:27]
	s_waitcnt lgkmcnt(1)
	v_mfma_f32_16x16x32_bf16 v[30:33], v[116:119], v[124:127], v[30:33]
	v_mfma_f32_16x16x32_bf16 v[26:29], v[120:123], v[124:127], v[26:29]
	v_mfma_f32_16x16x32_bf16 v[22:25], v[132:135], v[124:127], v[22:25]
	v_mfma_f32_16x16x32_bf16 v[18:21], v[136:139], v[124:127], v[18:21]
	s_add_u32 m0, s24, 0x3000
	s_nop 0
	global_load_lds_dwordx4 v107, s[26:27]
	s_waitcnt lgkmcnt(0)
	v_mfma_f32_16x16x32_bf16 v[14:17], v[116:119], v[128:131], v[14:17]
	v_mfma_f32_16x16x32_bf16 v[10:13], v[120:123], v[128:131], v[10:13]
	v_mfma_f32_16x16x32_bf16 v[6:9], v[132:135], v[128:131], v[6:9]
	v_mfma_f32_16x16x32_bf16 v[2:5], v[136:139], v[128:131], v[2:5]
	s_add_u32 s10, s10, 0x8000
	s_sub_u32 s25, s10, 0x14000
	s_cmp_ge_u32 s10, 0x14000
	s_cselect_b32 s10, s25, s10
	s_add_u32 s11, s11, 0x8000
	s_sub_u32 s25, s11, 0x14000
	s_cmp_ge_u32 s11, 0x14000
	s_cselect_b32 s11, s25, s11
	s_waitcnt vmcnt(4)
	s_barrier
	s_add_i32 s3, s3, 1
	s_cmp_lg_u32 s3, 14
	s_cbranch_scc1 .Lg1_loop
	s_add_i32 s32, s18, s48
	s_mov_b32 s40, 0
	s_cmp_lt_i32 s32, s12
	s_cbranch_scc0 .Lg1_tail_last
	s_and_b64 vcc, exec, s[50:51]
	s_cbranch_vccz .Lg1_nx_band
	s_mul_hi_i32 s33, s32, 0x92492493
	s_add_i32 s33, s33, s32
	s_lshr_b32 s34, s33, 31
	s_ashr_i32 s33, s33, 4
	s_add_i32 s34, s33, s34
	s_mul_i32 s33, s34, 28
	s_sub_i32 s35, s32, s33
	s_branch .Lg1_nx_done
.Lg1_nx_band:
	s_cmpk_gt_i32 s32, 0xfb
	s_cbranch_scc0 .Lg1_nx_lo
	s_add_i32 s33, s32, 0xffffff04
	s_and_b32 s34, s33, 7
	s_add_i32 s34, s13, s34
	s_lshr_b32 s35, s33, 3
	s_branch .Lg1_nx_done
.Lg1_nx_lo:
	s_mul_hi_i32 s33, s32, 0x38e38e39
	s_lshr_b32 s34, s33, 31
	s_ashr_i32 s33, s33, 1
	s_add_i32 s35, s33, s34
	s_mul_i32 s33, s35, 9
	s_sub_i32 s33, s32, s33
	s_add_i32 s34, s33, s19
.Lg1_nx_done:
	s_lshl_b32 s33, s34, 18
	s_add_u32 s36, s54, s33
	s_addc_u32 s37, s55, 0
	s_lshl_b32 s33, s35, 18
	s_add_u32 s38, s54, s33
	s_addc_u32 s39, s55, 0
	s_add_u32 s38, s38, 0xe680000
	s_addc_u32 s39, s39, 0
	s_mov_b32 s40, 1
	v_add_u32_e32 v136, s11, v100
	ds_read_b128 v[116:119], v136
	v_add_u32_e32 v115, s10, v98
	ds_read_b128 v[120:123], v136 offset:2048
	ds_read_b128 v[124:127], v115
	ds_read_b128 v[128:131], v115 offset:2048
	ds_read_b128 v[132:135], v136 offset:4096
	ds_read_b128 v[136:139], v136 offset:6144
	s_add_u32 s28, s28, 0x80
	s_addc_u32 s29, s29, 0
	s_add_u32 s31, s10, 0xc000
	s_sub_u32 s25, s31, 0x14000
	s_cmp_ge_u32 s31, 0x14000
	s_cselect_b32 s31, s25, s31
	s_add_u32 s31, s31, s30
	s_mov_b32 s26, s36
	s_mov_b32 s27, s37
	s_add_u32 s24, s10, 0x10000
	s_sub_u32 s25, s24, 0x14000
	s_cmp_ge_u32 s24, 0x14000
	s_cselect_b32 s24, s25, s24
	s_add_u32 s24, s24, s30
	s_mov_b32 m0, s31
	s_nop 0
	global_load_lds_dwordx4 v104, s[28:29]
	s_waitcnt lgkmcnt(3)
	v_mfma_f32_16x16x32_bf16 v[90:93], v[120:123], v[124:127], v[90:93]
	v_mfma_f32_16x16x32_bf16 v[94:97], v[116:119], v[124:127], v[94:97]
	s_waitcnt lgkmcnt(1)
	v_mfma_f32_16x16x32_bf16 v[86:89], v[132:135], v[124:127], v[86:89]
	s_waitcnt lgkmcnt(0)
	v_mfma_f32_16x16x32_bf16 v[82:85], v[136:139], v[124:127], v[82:85]
	s_add_u32 m0, s31, 0x1000
	s_nop 0
	global_load_lds_dwordx4 v105, s[28:29]
	v_mfma_f32_16x16x32_bf16 v[58:61], v[116:119], v[128:131], v[58:61]
	v_mfma_f32_16x16x32_bf16 v[50:53], v[120:123], v[128:131], v[50:53]
	v_mfma_f32_16x16x32_bf16 v[46:49], v[132:135], v[128:131], v[46:49]
	v_mfma_f32_16x16x32_bf16 v[34:37], v[136:139], v[128:131], v[34:37]
	ds_read_b128 v[124:127], v115 offset:4096
	ds_read_b128 v[128:131], v115 offset:6144
	v_add_u32_e32 v140, s11, v101
	s_add_u32 m0, s31, 0x2000
	s_nop 0
	global_load_lds_dwordx4 v106, s[28:29]
	s_waitcnt lgkmcnt(1)
	v_mfma_f32_16x16x32_bf16 v[30:33], v[116:119], v[124:127], v[30:33]
	v_add_u32_e32 v115, s10, v99
	v_mfma_f32_16x16x32_bf16 v[26:29], v[120:123], v[124:127], v[26:29]
	v_mfma_f32_16x16x32_bf16 v[22:25], v[132:135], v[124:127], v[22:25]
	v_mfma_f32_16x16x32_bf16 v[18:21], v[136:139], v[124:127], v[18:21]
	s_add_u32 m0, s31, 0x3000
	s_nop 0
	global_load_lds_dwordx4 v107, s[28:29]
	s_waitcnt lgkmcnt(0)
	v_mfma_f32_16x16x32_bf16 v[14:17], v[116:119], v[128:131], v[14:17]
	ds_read_b128 v[116:119], v140
	v_mfma_f32_16x16x32_bf16 v[10:13], v[120:123], v[128:131], v[10:13]
	v_mfma_f32_16x16x32_bf16 v[6:9], v[132:135], v[128:131], v[6:9]
	v_mfma_f32_16x16x32_bf16 v[2:5], v[136:139], v[128:131], v[2:5]
	ds_read_b128 v[120:123], v140 offset:2048
	ds_read_b128 v[124:127], v115
	ds_read_b128 v[128:131], v115 offset:2048
	ds_read_b128 v[132:135], v140 offset:4096
	ds_read_b128 v[136:139], v140 offset:6144
	s_mov_b32 m0, s24
	s_nop 0
	global_load_lds_dwordx4 v104, s[26:27]
	s_waitcnt lgkmcnt(3)
	v_mfma_f32_16x16x32_bf16 v[94:97], v[116:119], v[124:127], v[94:97]
	v_mfma_f32_16x16x32_bf16 v[90:93], v[120:123], v[124:127], v[90:93]
	s_waitcnt lgkmcnt(1)
	v_mfma_f32_16x16x32_bf16 v[86:89], v[132:135], v[124:127], v[86:89]
	s_waitcnt lgkmcnt(0)
	v_mfma_f32_16x16x32_bf16 v[82:85], v[136:139], v[124:127], v[82:85]
	s_add_u32 m0, s24, 0x1000
	s_nop 0
	global_load_lds_dwordx4 v105, s[26:27]
	v_mfma_f32_16x16x32_bf16 v[58:61], v[116:119], v[128:131], v[58:61]
	v_mfma_f32_16x16x32_bf16 v[50:53], v[120:123], v[128:131], v[50:53]
	v_mfma_f32_16x16x32_bf16 v[46:49], v[132:135], v[128:131], v[46:49]
	v_mfma_f32_16x16x32_bf16 v[34:37], v[136:139], v[128:131], v[34:37]
	ds_read_b128 v[124:127], v115 offset:4096
	ds_read_b128 v[128:131], v115 offset:6144
	s_add_u32 m0, s24, 0x2000
	s_nop 0
	global_load_lds_dwordx4 v106, s[26:27]
	s_waitcnt lgkmcnt(1)
	v_mfma_f32_16x16x32_bf16 v[30:33], v[116:119], v[124:127], v[30:33]
	v_mfma_f32_16x16x32_bf16 v[26:29], v[120:123], v[124:127], v[26:29]
	v_mfma_f32_16x16x32_bf16 v[22:25], v[132:135], v[124:127], v[22:25]
	v_mfma_f32_16x16x32_bf16 v[18:21], v[136:139], v[124:127], v[18:21]
	s_add_u32 m0, s24, 0x3000
	s_nop 0
	global_load_lds_dwordx4 v107, s[26:27]
	s_waitcnt lgkmcnt(0)
	v_mfma_f32_16x16x32_bf16 v[14:17], v[116:119], v[128:131], v[14:17]
	v_mfma_f32_16x16x32_bf16 v[10:13], v[120:123], v[128:131], v[10:13]
	v_mfma_f32_16x16x32_bf16 v[6:9], v[132:135], v[128:131], v[6:9]
	v_mfma_f32_16x16x32_bf16 v[2:5], v[136:139], v[128:131], v[2:5]
	s_add_u32 s10, s10, 0x8000
	s_sub_u32 s25, s10, 0x14000
	s_cmp_ge_u32 s10, 0x14000
	s_cselect_b32 s10, s25, s10
	s_add_u32 s11, s11, 0x8000
	s_sub_u32 s25, s11, 0x14000
	s_cmp_ge_u32 s11, 0x14000
	s_cselect_b32 s11, s25, s11
	s_waitcnt vmcnt(4)
	s_barrier
	v_add_u32_e32 v136, s11, v100
	ds_read_b128 v[116:119], v136
	v_add_u32_e32 v115, s10, v98
	ds_read_b128 v[120:123], v136 offset:2048
	ds_read_b128 v[124:127], v115
	ds_read_b128 v[128:131], v115 offset:2048
	ds_read_b128 v[132:135], v136 offset:4096
	ds_read_b128 v[136:139], v136 offset:6144
	s_mov_b32 s28, s38
	s_mov_b32 s29, s39
	s_add_u32 s31, s10, 0xc000
	s_sub_u32 s25, s31, 0x14000
	s_cmp_ge_u32 s31, 0x14000
	s_cselect_b32 s31, s25, s31
	s_add_u32 s31, s31, s30
	s_add_u32 s26, s26, 0x80
	s_addc_u32 s27, s27, 0
	s_add_u32 s24, s10, 0x10000
	s_sub_u32 s25, s24, 0x14000
	s_cmp_ge_u32 s24, 0x14000
	s_cselect_b32 s24, s25, s24
	s_add_u32 s24, s24, s30
	s_mov_b32 m0, s31
	s_nop 0
	global_load_lds_dwordx4 v104, s[28:29]
	s_waitcnt lgkmcnt(3)
	v_mfma_f32_16x16x32_bf16 v[90:93], v[120:123], v[124:127], v[90:93]
	v_mfma_f32_16x16x32_bf16 v[94:97], v[116:119], v[124:127], v[94:97]
	s_waitcnt lgkmcnt(1)
	v_mfma_f32_16x16x32_bf16 v[86:89], v[132:135], v[124:127], v[86:89]
	s_waitcnt lgkmcnt(0)
	v_mfma_f32_16x16x32_bf16 v[82:85], v[136:139], v[124:127], v[82:85]
	s_add_u32 m0, s31, 0x1000
	s_nop 0
	global_load_lds_dwordx4 v105, s[28:29]
	v_mfma_f32_16x16x32_bf16 v[58:61], v[116:119], v[128:131], v[58:61]
	v_mfma_f32_16x16x32_bf16 v[50:53], v[120:123], v[128:131], v[50:53]
	v_mfma_f32_16x16x32_bf16 v[46:49], v[132:135], v[128:131], v[46:49]
	v_mfma_f32_16x16x32_bf16 v[34:37], v[136:139], v[128:131], v[34:37]
	ds_read_b128 v[124:127], v115 offset:4096
	ds_read_b128 v[128:131], v115 offset:6144
	v_add_u32_e32 v140, s11, v101
	s_add_u32 m0, s31, 0x2000
	s_nop 0
	global_load_lds_dwordx4 v106, s[28:29]
	s_waitcnt lgkmcnt(1)
	v_mfma_f32_16x16x32_bf16 v[30:33], v[116:119], v[124:127], v[30:33]
	v_add_u32_e32 v115, s10, v99
	v_mfma_f32_16x16x32_bf16 v[26:29], v[120:123], v[124:127], v[26:29]
	v_mfma_f32_16x16x32_bf16 v[22:25], v[132:135], v[124:127], v[22:25]
	v_mfma_f32_16x16x32_bf16 v[18:21], v[136:139], v[124:127], v[18:21]
	s_add_u32 m0, s31, 0x3000
	s_nop 0
	global_load_lds_dwordx4 v107, s[28:29]
	s_waitcnt lgkmcnt(0)
	v_mfma_f32_16x16x32_bf16 v[14:17], v[116:119], v[128:131], v[14:17]
	ds_read_b128 v[116:119], v140
	v_mfma_f32_16x16x32_bf16 v[10:13], v[120:123], v[128:131], v[10:13]
	v_mfma_f32_16x16x32_bf16 v[6:9], v[132:135], v[128:131], v[6:9]
	v_mfma_f32_16x16x32_bf16 v[2:5], v[136:139], v[128:131], v[2:5]
	ds_read_b128 v[120:123], v140 offset:2048
	ds_read_b128 v[124:127], v115
	ds_read_b128 v[128:131], v115 offset:2048
	ds_read_b128 v[132:135], v140 offset:4096
	ds_read_b128 v[136:139], v140 offset:6144
	s_mov_b32 m0, s24
	s_nop 0
	global_load_lds_dwordx4 v104, s[26:27]
	s_waitcnt lgkmcnt(3)
	v_mfma_f32_16x16x32_bf16 v[94:97], v[116:119], v[124:127], v[94:97]
	v_mfma_f32_16x16x32_bf16 v[90:93], v[120:123], v[124:127], v[90:93]
	s_waitcnt lgkmcnt(1)
	v_mfma_f32_16x16x32_bf16 v[86:89], v[132:135], v[124:127], v[86:89]
	s_waitcnt lgkmcnt(0)
	v_mfma_f32_16x16x32_bf16 v[82:85], v[136:139], v[124:127], v[82:85]
	s_add_u32 m0, s24, 0x1000
	s_nop 0
	global_load_lds_dwordx4 v105, s[26:27]
	v_mfma_f32_16x16x32_bf16 v[58:61], v[116:119], v[128:131], v[58:61]
	v_mfma_f32_16x16x32_bf16 v[50:53], v[120:123], v[128:131], v[50:53]
	v_mfma_f32_16x16x32_bf16 v[46:49], v[132:135], v[128:131], v[46:49]
	v_mfma_f32_16x16x32_bf16 v[34:37], v[136:139], v[128:131], v[34:37]
	ds_read_b128 v[124:127], v115 offset:4096
	ds_read_b128 v[128:131], v115 offset:6144
	s_add_u32 m0, s24, 0x2000
	s_nop 0
	global_load_lds_dwordx4 v106, s[26:27]
	s_waitcnt lgkmcnt(1)
	v_mfma_f32_16x16x32_bf16 v[30:33], v[116:119], v[124:127], v[30:33]
	v_mfma_f32_16x16x32_bf16 v[26:29], v[120:123], v[124:127], v[26:29]
	v_mfma_f32_16x16x32_bf16 v[22:25], v[132:135], v[124:127], v[22:25]
	v_mfma_f32_16x16x32_bf16 v[18:21], v[136:139], v[124:127], v[18:21]
	s_add_u32 m0, s24, 0x3000
	s_nop 0
	global_load_lds_dwordx4 v107, s[26:27]
	s_waitcnt lgkmcnt(0)
	v_mfma_f32_16x16x32_bf16 v[14:17], v[116:119], v[128:131], v[14:17]
	v_mfma_f32_16x16x32_bf16 v[10:13], v[120:123], v[128:131], v[10:13]
	v_mfma_f32_16x16x32_bf16 v[6:9], v[132:135], v[128:131], v[6:9]
	v_mfma_f32_16x16x32_bf16 v[2:5], v[136:139], v[128:131], v[2:5]
	s_add_u32 s10, s10, 0x8000
	s_sub_u32 s25, s10, 0x14000
	s_cmp_ge_u32 s10, 0x14000
	s_cselect_b32 s10, s25, s10
	s_add_u32 s11, s11, 0x8000
	s_sub_u32 s25, s11, 0x14000
	s_cmp_ge_u32 s11, 0x14000
	s_cselect_b32 s11, s25, s11
	s_waitcnt vmcnt(4)
	s_barrier
	s_branch .LBB0_114
.Lg1_tail_last:
	v_add_u32_e32 v136, s11, v100
	ds_read_b128 v[116:119], v136
	v_add_u32_e32 v115, s10, v98
	ds_read_b128 v[120:123], v136 offset:2048
	ds_read_b128 v[124:127], v115
	ds_read_b128 v[128:131], v115 offset:2048
	ds_read_b128 v[132:135], v136 offset:4096
	ds_read_b128 v[136:139], v136 offset:6144
	s_add_u32 s28, s28, 0x80
	s_addc_u32 s29, s29, 0
	s_add_u32 s31, s10, 0xc000
	s_sub_u32 s25, s31, 0x14000
	s_cmp_ge_u32 s31, 0x14000
	s_cselect_b32 s31, s25, s31
	s_add_u32 s31, s31, s30
	s_mov_b32 m0, s31
	s_nop 0
	global_load_lds_dwordx4 v104, s[28:29]
	s_waitcnt lgkmcnt(3)
	v_mfma_f32_16x16x32_bf16 v[90:93], v[120:123], v[124:127], v[90:93]
	v_mfma_f32_16x16x32_bf16 v[94:97], v[116:119], v[124:127], v[94:97]
	s_waitcnt lgkmcnt(1)
	v_mfma_f32_16x16x32_bf16 v[86:89], v[132:135], v[124:127], v[86:89]
	s_waitcnt lgkmcnt(0)
	v_mfma_f32_16x16x32_bf16 v[82:85], v[136:139], v[124:127], v[82:85]
	s_add_u32 m0, s31, 0x1000
	s_nop 0
	global_load_lds_dwordx4 v105, s[28:29]
	v_mfma_f32_16x16x32_bf16 v[58:61], v[116:119], v[128:131], v[58:61]
	v_mfma_f32_16x16x32_bf16 v[50:53], v[120:123], v[128:131], v[50:53]
	v_mfma_f32_16x16x32_bf16 v[46:49], v[132:135], v[128:131], v[46:49]
	v_mfma_f32_16x16x32_bf16 v[34:37], v[136:139], v[128:131], v[34:37]
	ds_read_b128 v[124:127], v115 offset:4096
	ds_read_b128 v[128:131], v115 offset:6144
	v_add_u32_e32 v140, s11, v101
	s_add_u32 m0, s31, 0x2000
	s_nop 0
	global_load_lds_dwordx4 v106, s[28:29]
	s_waitcnt lgkmcnt(1)
	v_mfma_f32_16x16x32_bf16 v[30:33], v[116:119], v[124:127], v[30:33]
	v_add_u32_e32 v115, s10, v99
	v_mfma_f32_16x16x32_bf16 v[26:29], v[120:123], v[124:127], v[26:29]
	v_mfma_f32_16x16x32_bf16 v[22:25], v[132:135], v[124:127], v[22:25]
	v_mfma_f32_16x16x32_bf16 v[18:21], v[136:139], v[124:127], v[18:21]
	s_add_u32 m0, s31, 0x3000
	s_nop 0
	global_load_lds_dwordx4 v107, s[28:29]
	s_waitcnt lgkmcnt(0)
	v_mfma_f32_16x16x32_bf16 v[14:17], v[116:119], v[128:131], v[14:17]
	ds_read_b128 v[116:119], v140
	v_mfma_f32_16x16x32_bf16 v[10:13], v[120:123], v[128:131], v[10:13]
	v_mfma_f32_16x16x32_bf16 v[6:9], v[132:135], v[128:131], v[6:9]
	v_mfma_f32_16x16x32_bf16 v[2:5], v[136:139], v[128:131], v[2:5]
	ds_read_b128 v[120:123], v140 offset:2048
	ds_read_b128 v[124:127], v115
	ds_read_b128 v[128:131], v115 offset:2048
	ds_read_b128 v[132:135], v140 offset:4096
	ds_read_b128 v[136:139], v140 offset:6144
	s_waitcnt lgkmcnt(3)
	v_mfma_f32_16x16x32_bf16 v[94:97], v[116:119], v[124:127], v[94:97]
	v_mfma_f32_16x16x32_bf16 v[90:93], v[120:123], v[124:127], v[90:93]
	s_waitcnt lgkmcnt(1)
	v_mfma_f32_16x16x32_bf16 v[86:89], v[132:135], v[124:127], v[86:89]
	s_waitcnt lgkmcnt(0)
	v_mfma_f32_16x16x32_bf16 v[82:85], v[136:139], v[124:127], v[82:85]
	v_mfma_f32_16x16x32_bf16 v[58:61], v[116:119], v[128:131], v[58:61]
	v_mfma_f32_16x16x32_bf16 v[50:53], v[120:123], v[128:131], v[50:53]
	v_mfma_f32_16x16x32_bf16 v[46:49], v[132:135], v[128:131], v[46:49]
	v_mfma_f32_16x16x32_bf16 v[34:37], v[136:139], v[128:131], v[34:37]
	ds_read_b128 v[124:127], v115 offset:4096
	ds_read_b128 v[128:131], v115 offset:6144
	s_waitcnt lgkmcnt(1)
	v_mfma_f32_16x16x32_bf16 v[30:33], v[116:119], v[124:127], v[30:33]
	v_mfma_f32_16x16x32_bf16 v[26:29], v[120:123], v[124:127], v[26:29]
	v_mfma_f32_16x16x32_bf16 v[22:25], v[132:135], v[124:127], v[22:25]
	v_mfma_f32_16x16x32_bf16 v[18:21], v[136:139], v[124:127], v[18:21]
	s_waitcnt lgkmcnt(0)
	v_mfma_f32_16x16x32_bf16 v[14:17], v[116:119], v[128:131], v[14:17]
	v_mfma_f32_16x16x32_bf16 v[10:13], v[120:123], v[128:131], v[10:13]
	v_mfma_f32_16x16x32_bf16 v[6:9], v[132:135], v[128:131], v[6:9]
	v_mfma_f32_16x16x32_bf16 v[2:5], v[136:139], v[128:131], v[2:5]
	s_add_u32 s10, s10, 0x8000
	s_sub_u32 s25, s10, 0x14000
	s_cmp_ge_u32 s10, 0x14000
	s_cselect_b32 s10, s25, s10
	s_add_u32 s11, s11, 0x8000
	s_sub_u32 s25, s11, 0x14000
	s_cmp_ge_u32 s11, 0x14000
	s_cselect_b32 s11, s25, s11
	s_waitcnt vmcnt(0)
	s_barrier
	v_add_u32_e32 v136, s11, v100
	ds_read_b128 v[116:119], v136
	v_add_u32_e32 v115, s10, v98
	ds_read_b128 v[120:123], v136 offset:2048
	ds_read_b128 v[124:127], v115
	ds_read_b128 v[128:131], v115 offset:2048
	ds_read_b128 v[132:135], v136 offset:4096
	ds_read_b128 v[136:139], v136 offset:6144
	s_waitcnt lgkmcnt(3)
	v_mfma_f32_16x16x32_bf16 v[90:93], v[120:123], v[124:127], v[90:93]
	v_mfma_f32_16x16x32_bf16 v[94:97], v[116:119], v[124:127], v[94:97]
	s_waitcnt lgkmcnt(1)
	v_mfma_f32_16x16x32_bf16 v[86:89], v[132:135], v[124:127], v[86:89]
	s_waitcnt lgkmcnt(0)
	v_mfma_f32_16x16x32_bf16 v[82:85], v[136:139], v[124:127], v[82:85]
	v_mfma_f32_16x16x32_bf16 v[58:61], v[116:119], v[128:131], v[58:61]
	v_mfma_f32_16x16x32_bf16 v[50:53], v[120:123], v[128:131], v[50:53]
	v_mfma_f32_16x16x32_bf16 v[46:49], v[132:135], v[128:131], v[46:49]
	v_mfma_f32_16x16x32_bf16 v[34:37], v[136:139], v[128:131], v[34:37]
	ds_read_b128 v[124:127], v115 offset:4096
	ds_read_b128 v[128:131], v115 offset:6144
	v_add_u32_e32 v140, s11, v101
	s_waitcnt lgkmcnt(1)
	v_mfma_f32_16x16x32_bf16 v[30:33], v[116:119], v[124:127], v[30:33]
	v_add_u32_e32 v115, s10, v99
	v_mfma_f32_16x16x32_bf16 v[26:29], v[120:123], v[124:127], v[26:29]
	v_mfma_f32_16x16x32_bf16 v[22:25], v[132:135], v[124:127], v[22:25]
	v_mfma_f32_16x16x32_bf16 v[18:21], v[136:139], v[124:127], v[18:21]
	s_waitcnt lgkmcnt(0)
	v_mfma_f32_16x16x32_bf16 v[14:17], v[116:119], v[128:131], v[14:17]
	ds_read_b128 v[116:119], v140
	v_mfma_f32_16x16x32_bf16 v[10:13], v[120:123], v[128:131], v[10:13]
	v_mfma_f32_16x16x32_bf16 v[6:9], v[132:135], v[128:131], v[6:9]
	v_mfma_f32_16x16x32_bf16 v[2:5], v[136:139], v[128:131], v[2:5]
	ds_read_b128 v[120:123], v140 offset:2048
	ds_read_b128 v[124:127], v115
	ds_read_b128 v[128:131], v115 offset:2048
	ds_read_b128 v[132:135], v140 offset:4096
	ds_read_b128 v[136:139], v140 offset:6144
	s_waitcnt lgkmcnt(3)
	v_mfma_f32_16x16x32_bf16 v[94:97], v[116:119], v[124:127], v[94:97]
	v_mfma_f32_16x16x32_bf16 v[90:93], v[120:123], v[124:127], v[90:93]
	s_waitcnt lgkmcnt(1)
	v_mfma_f32_16x16x32_bf16 v[86:89], v[132:135], v[124:127], v[86:89]
	s_waitcnt lgkmcnt(0)
	v_mfma_f32_16x16x32_bf16 v[82:85], v[136:139], v[124:127], v[82:85]
	v_mfma_f32_16x16x32_bf16 v[58:61], v[116:119], v[128:131], v[58:61]
	v_mfma_f32_16x16x32_bf16 v[50:53], v[120:123], v[128:131], v[50:53]
	v_mfma_f32_16x16x32_bf16 v[46:49], v[132:135], v[128:131], v[46:49]
	v_mfma_f32_16x16x32_bf16 v[34:37], v[136:139], v[128:131], v[34:37]
	ds_read_b128 v[124:127], v115 offset:4096
	ds_read_b128 v[128:131], v115 offset:6144
	s_waitcnt lgkmcnt(1)
	v_mfma_f32_16x16x32_bf16 v[30:33], v[116:119], v[124:127], v[30:33]
	v_mfma_f32_16x16x32_bf16 v[26:29], v[120:123], v[124:127], v[26:29]
	v_mfma_f32_16x16x32_bf16 v[22:25], v[132:135], v[124:127], v[22:25]
	v_mfma_f32_16x16x32_bf16 v[18:21], v[136:139], v[124:127], v[18:21]
	s_waitcnt lgkmcnt(0)
	v_mfma_f32_16x16x32_bf16 v[14:17], v[116:119], v[128:131], v[14:17]
	v_mfma_f32_16x16x32_bf16 v[10:13], v[120:123], v[128:131], v[10:13]
	v_mfma_f32_16x16x32_bf16 v[6:9], v[132:135], v[128:131], v[6:9]
	v_mfma_f32_16x16x32_bf16 v[2:5], v[136:139], v[128:131], v[2:5]
	s_add_u32 s10, s10, 0x8000
	s_sub_u32 s25, s10, 0x14000
	s_cmp_ge_u32 s10, 0x14000
	s_cselect_b32 s10, s25, s10
	s_add_u32 s11, s11, 0x8000
	s_sub_u32 s25, s11, 0x14000
	s_cmp_ge_u32 s11, 0x14000
	s_cselect_b32 s11, s25, s11
	s_waitcnt vmcnt(0)
	s_barrier
	s_branch .LBB0_114

.LBB0_754:
	v_add_u32_e32 v98, s4, v2
	v_lshl_add_u64 v[94:95], v[6:7], 0, s[6:7]
	v_lshl_add_u64 v[96:97], v[8:9], 0, s[8:9]
	v_cmp_lt_i32_e32 vcc, s13, v98
	s_nop 1
	v_cndmask_b32_e32 v94, v94, v6, vcc
	v_cndmask_b32_e32 v95, v95, v7, vcc
	v_cndmask_b32_e32 v96, v96, v8, vcc
	v_cndmask_b32_e32 v97, v97, v9, vcc
	v_lshl_add_u64 v[30:31], v[8:9], 0, v[176:177]
	v_lshl_add_u64 v[26:27], v[6:7], 0, v[176:177]
	global_load_dwordx4 v[14:17], v[4:5], off offset:16
	global_load_dwordx4 v[18:21], v[4:5], off
	global_load_dwordx4 v[22:25], v[30:31], off
	v_add_co_u32_e32 v26, vcc, s5, v26
	s_nop 1
	v_addc_co_u32_e32 v27, vcc, 0, v27, vcc
	global_load_dwordx4 v[26:29], v[26:27], off offset:2048
	v_add_co_u32_e32 v30, vcc, 0x9900000, v30
	s_nop 1
	v_addc_co_u32_e32 v31, vcc, 0, v31, vcc
	v_lshl_add_u64 v[70:71], v[96:97], 0, v[176:177]
	v_lshl_add_u64 v[66:67], v[94:95], 0, v[176:177]
	global_load_dwordx4 v[54:57], v[4:5], off offset:16
	global_load_dwordx4 v[58:61], v[4:5], off
	global_load_dwordx4 v[62:65], v[70:71], off
	v_add_co_u32_e32 v66, vcc, s5, v66
	s_nop 1
	v_addc_co_u32_e32 v67, vcc, 0, v67, vcc
	global_load_dwordx4 v[66:69], v[66:67], off offset:2048
	v_add_co_u32_e32 v70, vcc, 0x9900000, v70
	s_nop 1
	v_addc_co_u32_e32 v71, vcc, 0, v71, vcc
	v_add_u32_e32 v2, s4, v2
	v_add_u32_e32 v2, s4, v2
	v_lshl_add_u64 v[6:7], v[6:7], 0, s[6:7]
	v_lshl_add_u64 v[6:7], v[6:7], 0, s[6:7]
	v_lshl_add_u64 v[8:9], v[8:9], 0, s[8:9]
	v_lshl_add_u64 v[8:9], v[8:9], 0, s[8:9]
	v_cmp_lt_i32_e64 s[0:1], s13, v2
	s_or_b64 s[10:11], s[0:1], s[10:11]
	s_waitcnt vmcnt(5)
	s_waitcnt vmcnt(1)
	v_lshlrev_b32_e32 v32, 16, v22
	v_lshlrev_b32_e32 v72, 16, v62
	v_and_b32_e32 v33, 0xffff0000, v22
	v_and_b32_e32 v73, 0xffff0000, v62
	v_lshlrev_b32_e32 v22, 16, v23
	v_lshlrev_b32_e32 v62, 16, v63
	v_and_b32_e32 v23, 0xffff0000, v23
	v_and_b32_e32 v63, 0xffff0000, v63
	v_pk_mul_f32 v[42:43], v[32:33], v[32:33]
	v_pk_mul_f32 v[82:83], v[72:73], v[72:73]
	v_pk_mul_f32 v[40:41], v[22:23], v[22:23]
	v_pk_mul_f32 v[80:81], v[62:63], v[62:63]
	s_waitcnt vmcnt(4)
	s_waitcnt vmcnt(0)
	v_lshlrev_b32_e32 v44, 16, v26
	v_lshlrev_b32_e32 v84, 16, v66
	v_and_b32_e32 v45, 0xffff0000, v26
	v_and_b32_e32 v85, 0xffff0000, v66
	v_lshlrev_b32_e32 v26, 16, v27
	v_lshlrev_b32_e32 v66, 16, v67
	v_and_b32_e32 v27, 0xffff0000, v27
	v_and_b32_e32 v67, 0xffff0000, v67
	v_lshlrev_b32_e32 v46, 16, v28
	v_lshlrev_b32_e32 v86, 16, v68
	v_and_b32_e32 v47, 0xffff0000, v28
	v_and_b32_e32 v87, 0xffff0000, v68
	v_add_f32_e32 v42, v42, v43
	v_add_f32_e32 v82, v82, v83
	v_lshlrev_b32_e32 v34, 16, v24
	v_lshlrev_b32_e32 v74, 16, v64
	v_and_b32_e32 v35, 0xffff0000, v24
	v_and_b32_e32 v75, 0xffff0000, v64
	v_mul_f32_e32 v43, 0xbfb8aa3b, v46
	v_mul_f32_e32 v83, 0xbfb8aa3b, v86
	v_mul_f32_e32 v48, 0xbfb8aa3b, v47
	v_mul_f32_e32 v88, 0xbfb8aa3b, v87
	v_mul_f32_e32 v49, 0xbfb8aa3b, v26
	v_mul_f32_e32 v89, 0xbfb8aa3b, v66
	v_mul_f32_e32 v50, 0xbfb8aa3b, v27
	v_mul_f32_e32 v90, 0xbfb8aa3b, v67
	v_mul_f32_e32 v51, 0xbfb8aa3b, v44
	v_mul_f32_e32 v91, 0xbfb8aa3b, v84
	v_add_f32_e32 v40, v42, v40
	v_add_f32_e32 v80, v82, v80
	v_pk_mul_f32 v[38:39], v[34:35], v[34:35]
	v_pk_mul_f32 v[78:79], v[74:75], v[74:75]
	v_lshlrev_b32_e32 v28, 16, v29
	v_lshlrev_b32_e32 v68, 16, v69
	v_mul_f32_e32 v52, 0xbfb8aa3b, v45
	v_mul_f32_e32 v92, 0xbfb8aa3b, v85
	v_exp_f32_e32 v43, v43
	v_exp_f32_e32 v83, v83
	v_exp_f32_e32 v48, v48
	v_exp_f32_e32 v88, v88
	v_exp_f32_e32 v49, v49
	v_exp_f32_e32 v89, v89
	v_exp_f32_e32 v50, v50
	v_exp_f32_e32 v90, v90
	v_exp_f32_e32 v51, v51
	v_exp_f32_e32 v91, v91
	v_add_f32_e32 v40, v41, v40
	v_add_f32_e32 v80, v81, v80
	v_lshlrev_b32_e32 v24, 16, v25
	v_lshlrev_b32_e32 v64, 16, v65
	v_and_b32_e32 v25, 0xffff0000, v25
	v_and_b32_e32 v65, 0xffff0000, v65
	v_mul_f32_e32 v42, 0xbfb8aa3b, v28
	v_mul_f32_e32 v82, 0xbfb8aa3b, v68
	v_exp_f32_e32 v52, v52
	v_exp_f32_e32 v92, v92
	v_add_f32_e32 v38, v38, v40
	v_add_f32_e32 v78, v78, v80
	v_pk_mul_f32 v[36:37], v[24:25], v[24:25]
	v_pk_mul_f32 v[76:77], v[64:65], v[64:65]
	v_exp_f32_e32 v41, v42
	v_exp_f32_e32 v81, v82
	v_add_f32_e32 v38, v39, v38
	v_add_f32_e32 v78, v79, v78
	v_add_f32_e32 v36, v36, v38
	v_add_f32_e32 v76, v76, v78
	v_add_f32_e32 v38, 1.0, v43
	v_add_f32_e32 v78, 1.0, v83
	v_add_f32_e32 v39, 1.0, v48
	v_add_f32_e32 v79, 1.0, v88
	v_add_f32_e32 v40, 1.0, v49
	v_add_f32_e32 v80, 1.0, v89
	v_add_f32_e32 v43, 1.0, v50
	v_add_f32_e32 v83, 1.0, v90
	v_add_f32_e32 v48, 1.0, v51
	v_add_f32_e32 v88, 1.0, v91
	v_add_f32_e32 v50, v37, v36
	v_add_f32_e32 v90, v77, v76
	v_add_f32_e32 v49, 1.0, v52
	v_add_f32_e32 v89, 1.0, v92
	v_rcp_f32_e32 v36, v38
	v_rcp_f32_e32 v76, v78
	v_rcp_f32_e32 v38, v40
	v_rcp_f32_e32 v78, v80
	v_rcp_f32_e32 v40, v48
	v_rcp_f32_e32 v80, v88
	ds_bpermute_b32 v48, v10, v50
	ds_bpermute_b32 v88, v10, v90
	v_add_f32_e32 v51, 1.0, v41
	v_add_f32_e32 v91, 1.0, v81
	v_rcp_f32_e32 v37, v39
	v_rcp_f32_e32 v77, v79
	v_rcp_f32_e32 v39, v43
	v_rcp_f32_e32 v79, v83
	v_rcp_f32_e32 v41, v49
	v_rcp_f32_e32 v81, v89
	v_and_b32_e32 v29, 0xffff0000, v29
	v_and_b32_e32 v69, 0xffff0000, v69
	v_mul_f32_e32 v53, 0xbfb8aa3b, v29
	v_mul_f32_e32 v93, 0xbfb8aa3b, v69
	v_pk_mul_f32 v[26:27], v[38:39], v[26:27]
	v_pk_mul_f32 v[66:67], v[78:79], v[66:67]
	v_pk_mul_f32 v[38:39], v[40:41], v[44:45]
	v_pk_mul_f32 v[78:79], v[80:81], v[84:85]
	s_waitcnt lgkmcnt(1)
	s_waitcnt lgkmcnt(0)
	v_add_f32_e32 v40, v50, v48
	v_add_f32_e32 v80, v90, v88
	ds_bpermute_b32 v41, v11, v40
	ds_bpermute_b32 v81, v11, v80
	v_exp_f32_e32 v42, v53
	v_exp_f32_e32 v82, v93
	v_pk_mul_f32 v[36:37], v[36:37], v[46:47]
	v_pk_mul_f32 v[76:77], v[76:77], v[86:87]
	s_waitcnt lgkmcnt(1)
	s_waitcnt lgkmcnt(0)
	v_add_f32_e32 v40, v40, v41
	v_add_f32_e32 v80, v80, v81
	ds_bpermute_b32 v41, v12, v40
	ds_bpermute_b32 v81, v12, v80
	v_add_f32_e32 v52, 1.0, v42
	v_add_f32_e32 v92, 1.0, v82
	v_rcp_f32_e32 v42, v51
	v_rcp_f32_e32 v82, v91
	v_rcp_f32_e32 v43, v52
	v_rcp_f32_e32 v83, v92
	s_waitcnt lgkmcnt(1)
	s_waitcnt lgkmcnt(0)
	v_add_f32_e32 v40, v40, v41
	v_add_f32_e32 v80, v80, v81
	ds_bpermute_b32 v41, v13, v40
	ds_bpermute_b32 v81, v13, v80
	v_pk_mul_f32 v[28:29], v[42:43], v[28:29]
	v_pk_mul_f32 v[68:69], v[82:83], v[68:69]
	s_waitcnt lgkmcnt(1)
	s_waitcnt lgkmcnt(0)
	v_add_f32_e32 v40, v40, v41
	v_add_f32_e32 v80, v80, v81
	v_fmamk_f32 v40, v40, 0x3c000000, v3
	v_fmamk_f32 v80, v80, 0x3c000000, v3
	v_mul_f32_e32 v41, 0x4b800000, v40
	v_mul_f32_e32 v81, 0x4b800000, v80
	v_cmp_gt_f32_e32 vcc, s12, v40
	v_cmp_gt_f32_e64 s[22:23], s12, v80
	s_nop 1
	s_nop 1
	v_cndmask_b32_e32 v40, v40, v41, vcc
	v_cndmask_b32_e64 v80, v80, v81, s[22:23]
	v_rsq_f32_e32 v40, v40
	v_rsq_f32_e32 v80, v80
	s_nop 0
	s_nop 0
	v_mul_f32_e32 v41, 0x45800000, v40
	v_mul_f32_e32 v81, 0x45800000, v80
	v_cndmask_b32_e32 v40, v40, v41, vcc
	v_cndmask_b32_e64 v80, v80, v81, s[22:23]
	v_pk_mul_f32 v[32:33], v[40:41], v[32:33] op_sel_hi:[0,1]
	v_pk_mul_f32 v[72:73], v[80:81], v[72:73] op_sel_hi:[0,1]
	v_pk_mul_f32 v[22:23], v[40:41], v[22:23] op_sel_hi:[0,1]
	v_pk_mul_f32 v[62:63], v[80:81], v[62:63] op_sel_hi:[0,1]
	v_pk_mul_f32 v[34:35], v[40:41], v[34:35] op_sel_hi:[0,1]
	v_pk_mul_f32 v[74:75], v[80:81], v[74:75] op_sel_hi:[0,1]
	v_pk_mul_f32 v[24:25], v[40:41], v[24:25] op_sel_hi:[0,1]
	v_pk_mul_f32 v[64:65], v[80:81], v[64:65] op_sel_hi:[0,1]
	v_pk_mul_f32 v[18:19], v[18:19], v[32:33]
	v_pk_mul_f32 v[58:59], v[58:59], v[72:73]
	v_pk_mul_f32 v[20:21], v[20:21], v[22:23]
	v_pk_mul_f32 v[60:61], v[60:61], v[62:63]
	v_pk_mul_f32 v[14:15], v[14:15], v[34:35]
	v_pk_mul_f32 v[54:55], v[54:55], v[74:75]
	v_pk_mul_f32 v[16:17], v[16:17], v[24:25]
	v_pk_mul_f32 v[56:57], v[56:57], v[64:65]
	v_pk_mul_f32 v[18:19], v[38:39], v[18:19]
	v_pk_mul_f32 v[58:59], v[78:79], v[58:59]
	v_pk_mul_f32 v[20:21], v[26:27], v[20:21]
	v_pk_mul_f32 v[60:61], v[66:67], v[60:61]
	v_pk_mul_f32 v[22:23], v[36:37], v[14:15]
	v_pk_mul_f32 v[62:63], v[76:77], v[54:55]
	v_pk_mul_f32 v[24:25], v[28:29], v[16:17]
	v_pk_mul_f32 v[64:65], v[68:69], v[56:57]
	v_cvt_pk_bf16_f32 v14, v18, v19
	v_cvt_pk_bf16_f32 v54, v58, v59
	v_cvt_pk_bf16_f32 v15, v20, v21
	v_cvt_pk_bf16_f32 v55, v60, v61
	v_cvt_pk_bf16_f32 v16, v22, v23
	v_cvt_pk_bf16_f32 v56, v62, v63
	v_cvt_pk_bf16_f32 v17, v24, v25
	v_cvt_pk_bf16_f32 v57, v64, v65
	global_store_dwordx4 v[30:31], v[14:17], off
	global_store_dwordx4 v[70:71], v[54:57], off
	s_andn2_b64 exec, exec, s[10:11]
	s_cbranch_execnz .LBB0_754
